# attention softmax: 16 v_pk_fma_f32 split into 32 scalar v_fma_f32 (asm guide 7.5 packed-vs-scalar), same f32 math
# baseline (speedup 1.0000x reference)
.LBB0_352:
	v_mul_f32_e32 v4, 0xbe0293ee, v228
	v_fma_f32 v7, v177, s10, v4
	v_fma_f32 v6, v176, s10, v4
	v_fma_f32 v9, v175, s10, v4
	v_fma_f32 v8, v174, s10, v4
	v_fma_f32 v11, v173, s10, v4
	v_fma_f32 v10, v172, s10, v4
	v_fma_f32 v13, v171, s10, v4
	v_fma_f32 v12, v170, s10, v4
	v_fma_f32 v15, v169, s10, v4
	v_fma_f32 v14, v168, s10, v4
	v_fma_f32 v17, v167, s10, v4
	v_fma_f32 v16, v166, s10, v4
	v_fma_f32 v165, v165, s10, v4
	v_fma_f32 v164, v164, s10, v4
	v_fma_f32 v163, v163, s10, v4
	v_fma_f32 v162, v162, s10, v4
	v_fma_f32 v161, v161, s10, v4
	v_fma_f32 v160, v160, s10, v4
	v_fma_f32 v159, v159, s10, v4
	v_fma_f32 v158, v158, s10, v4
	v_fma_f32 v157, v157, s10, v4
	v_fma_f32 v156, v156, s10, v4
	v_fma_f32 v155, v155, s10, v4
	v_fma_f32 v154, v154, s10, v4
	v_fma_f32 v153, v153, s10, v4
	v_fma_f32 v152, v152, s10, v4
	v_fma_f32 v151, v151, s10, v4
	v_fma_f32 v150, v150, s10, v4
	v_fma_f32 v149, v149, s10, v4
	v_fma_f32 v148, v148, s10, v4
	v_fma_f32 v5, v147, s10, v4
	v_fma_f32 v4, v146, s10, v4
	v_exp_f32_e32 v146, v162
	v_exp_f32_e32 v147, v4
	v_exp_f32_e32 v4, v163
	v_exp_f32_e32 v162, v5
	v_exp_f32_e32 v5, v164
	v_exp_f32_e32 v148, v148
	v_exp_f32_e32 v163, v165
	v_exp_f32_e32 v149, v149
	v_exp_f32_e32 v164, v16
	v_exp_f32_e32 v150, v150
	v_exp_f32_e32 v165, v17
	v_exp_f32_e32 v151, v151
	v_exp_f32_e32 v168, v6
	v_exp_f32_e32 v169, v7
	v_add_f32_e32 v6, v146, v147
	v_add_f32_e32 v7, v4, v162
	v_exp_f32_e32 v14, v14
	v_exp_f32_e32 v152, v152
	v_exp_f32_e32 v15, v15
	v_exp_f32_e32 v153, v153
	v_exp_f32_e32 v166, v8
	v_add_f32_e32 v6, v6, v7
	v_add_f32_e32 v7, v5, v148
	v_add_f32_e32 v8, v163, v149
	v_add_f32_e32 v6, 0, v6
	v_add_f32_e32 v7, v7, v8
	v_exp_f32_e32 v12, v12
	v_exp_f32_e32 v154, v154
	v_exp_f32_e32 v13, v13
	v_exp_f32_e32 v155, v155
	v_add_f32_e32 v6, v7, v6
	v_add_f32_e32 v7, v164, v150
	v_add_f32_e32 v8, v165, v151
	v_add_f32_e32 v7, v7, v8
	v_exp_f32_e32 v10, v10
	v_exp_f32_e32 v156, v156
	v_exp_f32_e32 v11, v11
	v_exp_f32_e32 v157, v157
	v_add_f32_e32 v6, v7, v6
	v_add_f32_e32 v7, v14, v152
	v_add_f32_e32 v8, v15, v153
	v_add_f32_e32 v7, v7, v8
	v_exp_f32_e32 v158, v158
	v_exp_f32_e32 v167, v9
	v_exp_f32_e32 v159, v159
	v_add_f32_e32 v6, v7, v6
	v_add_f32_e32 v7, v12, v154
	v_add_f32_e32 v8, v13, v155
	v_add_f32_e32 v7, v7, v8
	v_exp_f32_e32 v160, v160
	v_exp_f32_e32 v161, v161
	v_add_f32_e32 v6, v7, v6
	v_add_f32_e32 v7, v10, v156
	v_add_f32_e32 v8, v11, v157
	v_add_f32_e32 v7, v7, v8
	v_add_f32_e32 v6, v7, v6
	v_add_f32_e32 v7, v166, v158
	v_add_f32_e32 v8, v167, v159
	v_add_f32_e32 v7, v7, v8
	v_add_f32_e32 v6, v7, v6
	v_add_f32_e32 v7, v168, v160
	v_add_f32_e32 v8, v169, v161
	v_add_f32_e32 v7, v7, v8
	v_add_f32_e32 v16, v7, v6
	v_mov_b32_e32 v17, v16
	v_cvt_pk_bf16_f32 v4, v146, v4
	v_cvt_pk_bf16_f32 v5, v5, v163
	v_cvt_pk_bf16_f32 v6, v164, v165
	v_cvt_pk_bf16_f32 v7, v14, v15
	v_cvt_pk_bf16_f32 v8, v12, v13
	v_cvt_pk_bf16_f32 v9, v10, v11
	v_cvt_pk_bf16_f32 v10, v166, v167
	v_cvt_pk_bf16_f32 v11, v168, v169
	v_cvt_pk_bf16_f32 v146, v147, v162
	v_cvt_pk_bf16_f32 v147, v148, v149
	v_cvt_pk_bf16_f32 v148, v150, v151
	v_cvt_pk_bf16_f32 v149, v152, v153
	v_cvt_pk_bf16_f32 v12, v154, v155
	v_cvt_pk_bf16_f32 v13, v156, v157
	v_cvt_pk_bf16_f32 v14, v158, v159
	v_cvt_pk_bf16_f32 v15, v160, v161
	s_nop 1
	v_permlane32_swap_b32_e32 v16, v17
	v_permlane32_swap_b32_e32 v4, v6
	v_permlane32_swap_b32_e32 v5, v7
	v_permlane32_swap_b32_e32 v8, v10
	v_permlane32_swap_b32_e32 v9, v11
	v_permlane32_swap_b32_e32 v146, v148
	v_permlane32_swap_b32_e32 v147, v149
	v_permlane32_swap_b32_e32 v12, v14
	v_permlane32_swap_b32_e32 v13, v15
	v_cmp_gt_f32_e32 vcc, 1.0, v2
	s_cbranch_vccz .LBB0_354
	v_pk_mul_f32 v[144:145], v[144:145], v[2:3] op_sel_hi:[1,0]
	v_pk_mul_f32 v[142:143], v[142:143], v[2:3] op_sel_hi:[1,0]
	v_pk_mul_f32 v[140:141], v[140:141], v[2:3] op_sel_hi:[1,0]
	v_pk_mul_f32 v[138:139], v[138:139], v[2:3] op_sel_hi:[1,0]
	v_pk_mul_f32 v[136:137], v[136:137], v[2:3] op_sel_hi:[1,0]
	v_pk_mul_f32 v[134:135], v[134:135], v[2:3] op_sel_hi:[1,0]
	v_pk_mul_f32 v[132:133], v[132:133], v[2:3] op_sel_hi:[1,0]
	v_pk_mul_f32 v[130:131], v[130:131], v[2:3] op_sel_hi:[1,0]
	v_pk_mul_f32 v[128:129], v[128:129], v[2:3] op_sel_hi:[1,0]
	v_pk_mul_f32 v[126:127], v[126:127], v[2:3] op_sel_hi:[1,0]
	v_pk_mul_f32 v[124:125], v[124:125], v[2:3] op_sel_hi:[1,0]
	v_pk_mul_f32 v[122:123], v[122:123], v[2:3] op_sel_hi:[1,0]
	v_pk_mul_f32 v[120:121], v[120:121], v[2:3] op_sel_hi:[1,0]
	v_pk_mul_f32 v[118:119], v[118:119], v[2:3] op_sel_hi:[1,0]
	v_pk_mul_f32 v[116:117], v[116:117], v[2:3] op_sel_hi:[1,0]
	v_pk_mul_f32 v[114:115], v[114:115], v[2:3] op_sel_hi:[1,0]
	v_pk_mul_f32 v[112:113], v[112:113], v[2:3] op_sel_hi:[1,0]
	v_pk_mul_f32 v[110:111], v[110:111], v[2:3] op_sel_hi:[1,0]
	v_pk_mul_f32 v[108:109], v[108:109], v[2:3] op_sel_hi:[1,0]
	v_pk_mul_f32 v[106:107], v[106:107], v[2:3] op_sel_hi:[1,0]
	v_pk_mul_f32 v[104:105], v[104:105], v[2:3] op_sel_hi:[1,0]
	v_pk_mul_f32 v[102:103], v[102:103], v[2:3] op_sel_hi:[1,0]
	v_pk_mul_f32 v[100:101], v[100:101], v[2:3] op_sel_hi:[1,0]
	v_pk_mul_f32 v[98:99], v[98:99], v[2:3] op_sel_hi:[1,0]
	v_pk_mul_f32 v[96:97], v[96:97], v[2:3] op_sel_hi:[1,0]
	v_pk_mul_f32 v[94:95], v[94:95], v[2:3] op_sel_hi:[1,0]
	v_pk_mul_f32 v[92:93], v[92:93], v[2:3] op_sel_hi:[1,0]
	v_pk_mul_f32 v[90:91], v[90:91], v[2:3] op_sel_hi:[1,0]
	v_pk_mul_f32 v[88:89], v[88:89], v[2:3] op_sel_hi:[1,0]
	v_pk_mul_f32 v[86:87], v[86:87], v[2:3] op_sel_hi:[1,0]
	v_pk_mul_f32 v[84:85], v[84:85], v[2:3] op_sel_hi:[1,0]
	v_pk_mul_f32 v[82:83], v[82:83], v[2:3] op_sel_hi:[1,0]
	v_pk_mul_f32 v[80:81], v[80:81], v[2:3] op_sel_hi:[1,0]
	v_pk_mul_f32 v[78:79], v[78:79], v[2:3] op_sel_hi:[1,0]
	v_pk_mul_f32 v[76:77], v[76:77], v[2:3] op_sel_hi:[1,0]
	v_pk_mul_f32 v[74:75], v[74:75], v[2:3] op_sel_hi:[1,0]
	v_pk_mul_f32 v[72:73], v[72:73], v[2:3] op_sel_hi:[1,0]
	v_pk_mul_f32 v[70:71], v[70:71], v[2:3] op_sel_hi:[1,0]
	v_pk_mul_f32 v[68:69], v[68:69], v[2:3] op_sel_hi:[1,0]
	v_pk_mul_f32 v[66:67], v[66:67], v[2:3] op_sel_hi:[1,0]
	v_pk_mul_f32 v[64:65], v[64:65], v[2:3] op_sel_hi:[1,0]
	v_pk_mul_f32 v[62:63], v[62:63], v[2:3] op_sel_hi:[1,0]
	v_pk_mul_f32 v[60:61], v[60:61], v[2:3] op_sel_hi:[1,0]
	v_pk_mul_f32 v[58:59], v[58:59], v[2:3] op_sel_hi:[1,0]
	v_pk_mul_f32 v[56:57], v[56:57], v[2:3] op_sel_hi:[1,0]
	v_pk_mul_f32 v[54:55], v[54:55], v[2:3] op_sel_hi:[1,0]
	v_pk_mul_f32 v[52:53], v[52:53], v[2:3] op_sel_hi:[1,0]
	v_pk_mul_f32 v[50:51], v[50:51], v[2:3] op_sel_hi:[1,0]
	v_pk_mul_f32 v[48:49], v[48:49], v[2:3] op_sel_hi:[1,0]
	v_pk_mul_f32 v[46:47], v[46:47], v[2:3] op_sel_hi:[1,0]
	v_pk_mul_f32 v[44:45], v[44:45], v[2:3] op_sel_hi:[1,0]
	v_pk_mul_f32 v[42:43], v[42:43], v[2:3] op_sel_hi:[1,0]
	v_pk_mul_f32 v[40:41], v[40:41], v[2:3] op_sel_hi:[1,0]
	v_pk_mul_f32 v[38:39], v[38:39], v[2:3] op_sel_hi:[1,0]
	v_pk_mul_f32 v[36:37], v[36:37], v[2:3] op_sel_hi:[1,0]
	v_pk_mul_f32 v[34:35], v[34:35], v[2:3] op_sel_hi:[1,0]
	v_pk_mul_f32 v[32:33], v[32:33], v[2:3] op_sel_hi:[1,0]
	v_pk_mul_f32 v[30:31], v[30:31], v[2:3] op_sel_hi:[1,0]
	v_pk_mul_f32 v[28:29], v[28:29], v[2:3] op_sel_hi:[1,0]
	v_pk_mul_f32 v[26:27], v[26:27], v[2:3] op_sel_hi:[1,0]
	v_pk_mul_f32 v[24:25], v[24:25], v[2:3] op_sel_hi:[1,0]
	v_pk_mul_f32 v[22:23], v[22:23], v[2:3] op_sel_hi:[1,0]
	v_pk_mul_f32 v[20:21], v[20:21], v[2:3] op_sel_hi:[1,0]
	v_pk_mul_f32 v[18:19], v[18:19], v[2:3] op_sel_hi:[1,0]
